# ssd_s1 causal-conv loop: four taps of a row loaded together one row ahead (same change as ssd_s3 B/X loops)
# baseline (speedup 1.0000x reference)
.LBB0_621:
	s_or_b64 exec, exec, s[30:31]
	s_waitcnt lgkmcnt(0)
	s_barrier
	s_and_saveexec_b64 s[30:31], s[24:25]
	s_cbranch_execz .LBB0_634
	v_readlane_b32 s4, v242, 22
	v_readlane_b32 s5, v242, 23
	s_lshl_b64 s[4:5], s[4:5], 2
	v_readlane_b32 s50, v242, 24
	s_add_u32 s4, s62, s4
	v_readlane_b32 s51, v242, 25
	s_addc_u32 s5, s63, s5
	s_lshl_b64 s[50:51], s[50:51], 2
	s_add_u32 s40, s40, s50
	s_addc_u32 s41, s41, s51
	s_lshl_b32 s38, s55, 7
	v_or_b32_e32 v46, s38, v69
	v_add_u32_e32 v2, s38, v144
	v_cndmask_b32_e64 v2, v2, v46, s[22:23]
	v_lshlrev_b32_e32 v24, 2, v2
	v_mov_b32_e32 v25, v11
	v_lshl_add_u64 v[28:29], s[4:5], 0, v[24:25]
	global_load_dwordx4 v[2:5], v24, s[40:41] offset:16
	global_load_dwordx4 v[6:9], v24, s[40:41]
	global_load_dwordx4 v[12:15], v24, s[4:5] offset:16
	global_load_dwordx4 v[16:19], v24, s[4:5]
	global_load_dwordx4 v[20:23], v24, s[4:5] offset:3088
	s_nop 0
	global_load_dwordx4 v[24:27], v24, s[4:5] offset:3072
	s_movk_i32 s4, 0x1000
	v_add_co_u32_e32 v30, vcc, s4, v28
	s_mov_b64 s[50:51], 0x1800
	s_nop 0
	v_addc_co_u32_e32 v31, vcc, 0, v29, vcc
	s_movk_i32 s4, 0x2000
	v_lshl_add_u64 v[36:37], v[28:29], 0, s[50:51]
	s_mov_b64 s[50:51], 0x2400
	v_add_co_u32_e32 v32, vcc, s4, v28
	v_lshl_add_u64 v[40:41], v[28:29], 0, s[50:51]
	s_nop 0
	v_addc_co_u32_e32 v33, vcc, 0, v29, vcc
	global_load_dwordx4 v[28:31], v[30:31], off offset:2048
	s_nop 0
	global_load_dwordx4 v[32:35], v[32:33], off offset:1024
	s_nop 0
	global_load_dwordx4 v[36:39], v[36:37], off offset:16
	s_nop 0
	global_load_dwordx4 v[40:43], v[40:41], off offset:16
	s_lshl_b32 s4, s96, 7
	s_lshr_b32 s40, s47, 7
	s_mov_b32 s41, s49
	s_and_b32 s4, s4, 0x3f00
	s_lshl_b64 s[40:41], s[40:41], 14
	v_or_b32_e32 v46, 0x800, v46
	v_add_u32_e32 v47, s38, v146
	s_or_b32 s40, s40, s4
	v_cndmask_b32_e64 v46, v47, v46, s[22:23]
	ds_read_b32 v54, v145 offset:1020
	v_lshl_add_u64 v[44:45], s[40:41], 0, v[70:71]
	v_lshlrev_b32_e32 v46, 1, v46
	v_mov_b32_e32 v47, v11
	v_mad_u64_u32 v[46:47], s[40:41], v44, s64, v[46:47]
	v_mad_i32_i24 v47, v45, s64, v47
	v_lshl_add_u64 v[44:45], s[34:35], 0, v[46:47]
	s_mov_b64 s[40:41], 0x97fb800
	v_lshl_add_u64 v[44:45], v[44:45], 0, s[40:41]
	s_mov_b64 s[40:41], 0
	v_mov_b32_e32 v55, v158
	v_mov_b32_e32 v56, v157
	v_mov_b32_e32 v57, v70
	s_add_u32 s98, s94, 0x1000
	s_addc_u32 s99, s95, 0
	v_mov_b32_e32 v236, 0x3000
	v_mov_b32_e32 v237, 0
	v_add_co_u32_e32 v198, vcc, 0x1000, v44
	v_addc_co_u32_e32 v199, vcc, 0, v45, vcc
	v_add_co_u32_e32 v200, vcc, 0x4000, v44
	v_addc_co_u32_e32 v201, vcc, 0, v45, vcc
	global_load_dwordx4 v[214:217], v[198:199], off offset:-4096
	global_load_dwordx4 v[218:221], v[198:199], off offset:2048
	global_load_dwordx4 v[222:225], v[200:201], off offset:-4096
	global_load_dwordx4 v[226:229], v[200:201], off offset:2048
	s_branch .LBB0_624

.LBB0_624:
	s_waitcnt vmcnt(0)
	v_mov_b64_e32 v[182:183], v[214:215]
	v_mov_b64_e32 v[184:185], v[216:217]
	v_mov_b64_e32 v[186:187], v[218:219]
	v_mov_b64_e32 v[188:189], v[220:221]
	v_mov_b64_e32 v[190:191], v[222:223]
	v_mov_b64_e32 v[192:193], v[224:225]
	v_mov_b64_e32 v[194:195], v[226:227]
	v_mov_b64_e32 v[196:197], v[228:229]
	v_lshl_add_u64 v[198:199], v[44:45], 0, s[98:99]
	v_lshl_add_u64 v[200:201], v[198:199], 0, v[236:237]
	global_load_dwordx4 v[214:217], v[198:199], off offset:-4096
	global_load_dwordx4 v[218:221], v[198:199], off offset:2048
	global_load_dwordx4 v[222:225], v[200:201], off offset:-4096
	global_load_dwordx4 v[226:229], v[200:201], off offset:2048
	v_add_u32_e32 v58, s4, v57
	v_cmp_lt_i32_e32 vcc, 2, v58
	v_mov_b64_e32 v[52:53], v[6:7]
	v_mov_b64_e32 v[50:51], v[8:9]
	v_mov_b64_e32 v[48:49], v[2:3]
	v_mov_b64_e32 v[46:47], v[4:5]
	s_and_saveexec_b64 s[62:63], vcc
	s_cbranch_execnz .LBB0_631
	s_or_b64 exec, exec, s[62:63]
	v_cmp_lt_i32_e32 vcc, 1, v58
	s_and_saveexec_b64 s[62:63], vcc
	s_cbranch_execnz .LBB0_632

.LBB0_628:
	v_and_b32_e32 v59, 0xffff0000, v194
	v_lshlrev_b32_e32 v58, 16, v194
	v_pk_fma_f32 v[52:53], v[32:33], v[58:59], v[52:53]
	v_and_b32_e32 v59, 0xffff0000, v195
	v_lshlrev_b32_e32 v58, 16, v195
	v_pk_fma_f32 v[50:51], v[34:35], v[58:59], v[50:51]
	v_and_b32_e32 v59, 0xffff0000, v196
	v_lshlrev_b32_e32 v58, 16, v196
	v_pk_fma_f32 v[48:49], v[40:41], v[58:59], v[48:49]
	v_and_b32_e32 v59, 0xffff0000, v197
	v_lshlrev_b32_e32 v58, 16, v197
	v_pk_fma_f32 v[46:47], v[42:43], v[58:59], v[46:47]

.LBB0_631:
	v_and_b32_e32 v51, 0xffff0000, v182
	v_lshlrev_b32_e32 v50, 16, v182
	v_and_b32_e32 v167, 0xffff0000, v183
	v_lshlrev_b32_e32 v166, 16, v183
	v_and_b32_e32 v47, 0xffff0000, v184
	v_lshlrev_b32_e32 v46, 16, v184
	v_and_b32_e32 v169, 0xffff0000, v185
	v_lshlrev_b32_e32 v168, 16, v185
	v_pk_fma_f32 v[52:53], v[16:17], v[50:51], v[6:7]
	v_pk_fma_f32 v[50:51], v[18:19], v[166:167], v[8:9]
	v_pk_fma_f32 v[48:49], v[12:13], v[46:47], v[2:3]
	v_pk_fma_f32 v[46:47], v[14:15], v[168:169], v[4:5]
	s_or_b64 exec, exec, s[62:63]
	v_cmp_lt_i32_e32 vcc, 1, v58
	s_and_saveexec_b64 s[62:63], vcc
	s_cbranch_execz .LBB0_626
.LBB0_632:
	v_and_b32_e32 v171, 0xffff0000, v186
	v_lshlrev_b32_e32 v170, 16, v186
	v_pk_fma_f32 v[52:53], v[24:25], v[170:171], v[52:53]
	v_and_b32_e32 v171, 0xffff0000, v187
	v_lshlrev_b32_e32 v170, 16, v187
	v_and_b32_e32 v167, 0xffff0000, v188
	v_lshlrev_b32_e32 v166, 16, v188
	v_pk_fma_f32 v[48:49], v[20:21], v[166:167], v[48:49]
	v_and_b32_e32 v167, 0xffff0000, v189
	v_lshlrev_b32_e32 v166, 16, v189
	v_pk_fma_f32 v[50:51], v[26:27], v[170:171], v[50:51]
	v_pk_fma_f32 v[46:47], v[22:23], v[166:167], v[46:47]
	s_or_b64 exec, exec, s[62:63]
	v_cmp_lt_i32_e32 vcc, 0, v58
	s_and_saveexec_b64 s[62:63], vcc
	s_cbranch_execz .LBB0_627
.LBB0_633:
	v_and_b32_e32 v171, 0xffff0000, v190
	v_lshlrev_b32_e32 v170, 16, v190
	v_pk_fma_f32 v[52:53], v[28:29], v[170:171], v[52:53]
	v_and_b32_e32 v171, 0xffff0000, v191
	v_lshlrev_b32_e32 v170, 16, v191
	v_and_b32_e32 v167, 0xffff0000, v192
	v_lshlrev_b32_e32 v166, 16, v192
	v_pk_fma_f32 v[48:49], v[36:37], v[166:167], v[48:49]
	v_and_b32_e32 v167, 0xffff0000, v193
	v_lshlrev_b32_e32 v166, 16, v193
	v_pk_fma_f32 v[50:51], v[30:31], v[170:171], v[50:51]
	v_pk_fma_f32 v[46:47], v[38:39], v[166:167], v[46:47]
	s_or_b64 exec, exec, s[62:63]
	v_cmp_lt_i32_e32 vcc, -1, v58
	s_and_saveexec_b64 s[62:63], vcc
	s_cbranch_execnz .LBB0_628
	s_branch .LBB0_629
.LBB0_634:
	s_waitcnt vmcnt(0)
	s_or_b64 exec, exec, s[30:31]
	s_waitcnt lgkmcnt(0)
	s_barrier
	ds_read_u16 v2, v147 offset:256
	ds_read_u16 v6, v147 offset:772
	ds_read_u16 v3, v147 offset:1288
	ds_read_u16 v7, v147 offset:1804
	ds_read_u16 v4, v147 offset:2320
	ds_read_u16 v8, v147 offset:2836
	ds_read_u16 v5, v147 offset:3352
	ds_read_u16 v9, v147 offset:3868
	s_waitcnt vmcnt(7)
	ds_read_u16 v12, v147 offset:288
	ds_read_u16 v13, v147 offset:804
	ds_read_u16 v14, v147 offset:1320
	ds_read_u16 v15, v147 offset:1836
	s_waitcnt vmcnt(6)
	ds_read_u16 v16, v147 offset:2352
	ds_read_u16 v17, v147 offset:2868
	ds_read_u16 v18, v147 offset:3384
	ds_read_u16 v19, v147 offset:3900
	s_waitcnt lgkmcnt(8)
	v_perm_b32 v5, v9, v5, s43
	v_perm_b32 v4, v8, v4, s43
	v_perm_b32 v3, v7, v3, s43
	v_perm_b32 v2, v6, v2, s43
	s_waitcnt lgkmcnt(0)
	v_perm_b32 v9, v19, v18, s43
	v_perm_b32 v8, v17, v16, s43
	v_perm_b32 v7, v15, v14, s43
	v_perm_b32 v6, v13, v12, s43
	ds_read_u16 v12, v148
	ds_read_u16 v16, v148 offset:516
	ds_read_u16 v13, v148 offset:1032
	ds_read_u16 v17, v148 offset:1548
	ds_read_u16 v14, v148 offset:2064
	ds_read_u16 v18, v148 offset:2580
	ds_read_u16 v15, v148 offset:3096
	ds_read_u16 v19, v148 offset:3612
	s_waitcnt lgkmcnt(4)
	v_perm_b32 v13, v17, v13, s43
	v_perm_b32 v12, v16, v12, s43
	s_waitcnt lgkmcnt(2)
	v_perm_b32 v14, v18, v14, s43
	s_lshl_b32 s4, s55, 1
	s_waitcnt lgkmcnt(0)
	v_perm_b32 v15, v19, v15, s43
	s_mov_b32 s5, s49
	s_lshl_b32 s2, s2, 17
	s_waitcnt vmcnt(1)
	v_mfma_f32_16x16x32_bf16 v[36:39], v[12:15], v[2:5], 0
	v_mov_b32_e32 v81, v11
	v_mov_b32_e32 v83, v11
	v_mov_b32_e32 v85, v11
	s_waitcnt vmcnt(0)
	v_mfma_f32_16x16x32_bf16 v[40:43], v[12:15], v[6:9], 0
	ds_read_u16 v12, v148 offset:32
	ds_read_u16 v16, v148 offset:548
	ds_read_u16 v13, v148 offset:1064
	ds_read_u16 v17, v148 offset:1580
	ds_read_u16 v14, v148 offset:2096
	ds_read_u16 v18, v148 offset:2612
	ds_read_u16 v15, v148 offset:3128
	ds_read_u16 v19, v148 offset:3644
	s_waitcnt lgkmcnt(4)
	v_perm_b32 v13, v17, v13, s43
	v_perm_b32 v12, v16, v12, s43
	s_waitcnt lgkmcnt(2)
	v_perm_b32 v14, v18, v14, s43
	v_mov_b32_e32 v87, v11
	s_waitcnt lgkmcnt(0)
	v_perm_b32 v15, v19, v15, s43
	v_mov_b32_e32 v89, v11
	v_mov_b32_e32 v91, v11
	v_mfma_f32_16x16x32_bf16 v[28:31], v[12:15], v[2:5], 0
	v_mov_b32_e32 v93, v11
	v_mov_b32_e32 v95, v11
	v_mov_b32_e32 v97, v11
	v_mfma_f32_16x16x32_bf16 v[32:35], v[12:15], v[6:9], 0
	ds_read_u16 v12, v148 offset:64
	ds_read_u16 v16, v148 offset:580
	ds_read_u16 v13, v148 offset:1096
	ds_read_u16 v17, v148 offset:1612
	ds_read_u16 v14, v148 offset:2128
	ds_read_u16 v18, v148 offset:2644
	ds_read_u16 v15, v148 offset:3160
	ds_read_u16 v19, v148 offset:3676
	s_waitcnt lgkmcnt(4)
	v_perm_b32 v13, v17, v13, s43
	v_perm_b32 v12, v16, v12, s43
	s_waitcnt lgkmcnt(2)
	v_perm_b32 v14, v18, v14, s43
	v_mov_b32_e32 v99, v11
	s_waitcnt lgkmcnt(0)
	v_perm_b32 v15, v19, v15, s43
	v_mov_b32_e32 v101, v11
	v_mov_b32_e32 v103, v11
	v_mfma_f32_16x16x32_bf16 v[20:23], v[12:15], v[2:5], 0
	v_mov_b32_e32 v105, v11
	v_mov_b32_e32 v107, v11
	v_mov_b32_e32 v109, v11
	v_mfma_f32_16x16x32_bf16 v[24:27], v[12:15], v[6:9], 0
	ds_read_u16 v12, v148 offset:96
	ds_read_u16 v16, v148 offset:612
	ds_read_u16 v13, v148 offset:1128
	ds_read_u16 v17, v148 offset:1644
	ds_read_u16 v14, v148 offset:2160
	ds_read_u16 v18, v148 offset:2676
	ds_read_u16 v15, v148 offset:3192
	ds_read_u16 v19, v148 offset:3708
	s_waitcnt lgkmcnt(4)
	v_perm_b32 v13, v17, v13, s43
	v_perm_b32 v12, v16, v12, s43
	s_waitcnt lgkmcnt(2)
	v_perm_b32 v14, v18, v14, s43
	v_mov_b32_e32 v111, v11
	s_waitcnt lgkmcnt(0)
	v_perm_b32 v15, v19, v15, s43
	s_nop 1
	v_mfma_f32_16x16x32_bf16 v[2:5], v[12:15], v[2:5], 0
	v_mfma_f32_16x16x32_bf16 v[6:9], v[12:15], v[6:9], 0
	ds_read_u16 v12, v147 offset:16768
	ds_read_u16 v16, v147 offset:17284
	ds_read_u16 v13, v147 offset:17800
	ds_read_u16 v17, v147 offset:18316
	ds_read_u16 v14, v147 offset:18832
	ds_read_u16 v18, v147 offset:19348
	ds_read_u16 v15, v147 offset:19864
	ds_read_u16 v19, v147 offset:20380
	ds_read_u16 v44, v147 offset:16800
	ds_read_u16 v45, v147 offset:17316
	ds_read_u16 v46, v147 offset:17832
	ds_read_u16 v47, v147 offset:18348
	ds_read_u16 v48, v147 offset:18864
	ds_read_u16 v49, v147 offset:19380
	ds_read_u16 v50, v147 offset:19896
	ds_read_u16 v51, v147 offset:20412
	s_waitcnt lgkmcnt(8)
	v_perm_b32 v15, v19, v15, s43
	v_perm_b32 v14, v18, v14, s43
	v_perm_b32 v13, v17, v13, s43
	v_perm_b32 v12, v16, v12, s43
	s_waitcnt lgkmcnt(0)
	v_perm_b32 v19, v51, v50, s43
	v_perm_b32 v18, v49, v48, s43
	v_perm_b32 v17, v47, v46, s43
	v_perm_b32 v16, v45, v44, s43
	ds_read_u16 v44, v148 offset:16512
	ds_read_u16 v45, v148 offset:17028
	ds_read_u16 v46, v148 offset:17544
	ds_read_u16 v47, v148 offset:18060
	ds_read_u16 v48, v148 offset:18576
	ds_read_u16 v49, v148 offset:19092
	ds_read_u16 v50, v148 offset:19608
	ds_read_u16 v51, v148 offset:20124
	s_waitcnt lgkmcnt(0)
	v_perm_b32 v51, v51, v50, s43
	v_perm_b32 v50, v49, v48, s43
	v_perm_b32 v49, v47, v46, s43
	v_perm_b32 v48, v45, v44, s43
	s_nop 1
	v_mfma_f32_16x16x32_bf16 v[44:47], v[48:51], v[12:15], v[36:39]
	v_mfma_f32_16x16x32_bf16 v[48:51], v[48:51], v[16:19], v[40:43]
	s_nop 1
	ds_read_u16 v36, v148 offset:16544
	ds_read_u16 v40, v148 offset:17060
	ds_read_u16 v37, v148 offset:17576
	ds_read_u16 v41, v148 offset:18092
	ds_read_u16 v38, v148 offset:18608
	ds_read_u16 v42, v148 offset:19124
	ds_read_u16 v39, v148 offset:19640
	ds_read_u16 v43, v148 offset:20156
	s_waitcnt lgkmcnt(4)
	v_perm_b32 v37, v41, v37, s43
	v_perm_b32 v36, v40, v36, s43
	s_waitcnt lgkmcnt(2)
	v_perm_b32 v38, v42, v38, s43
	s_waitcnt lgkmcnt(0)
	v_perm_b32 v39, v43, v39, s43
	s_nop 1
	v_mfma_f32_16x16x32_bf16 v[52:55], v[36:39], v[12:15], v[28:31]
	v_mfma_f32_16x16x32_bf16 v[56:59], v[36:39], v[16:19], v[32:35]
	s_nop 1
	ds_read_u16 v28, v148 offset:16576
	ds_read_u16 v32, v148 offset:17092
	ds_read_u16 v29, v148 offset:17608
	ds_read_u16 v33, v148 offset:18124
	ds_read_u16 v30, v148 offset:18640
	ds_read_u16 v34, v148 offset:19156
	ds_read_u16 v31, v148 offset:19672
	ds_read_u16 v35, v148 offset:20188
	s_waitcnt lgkmcnt(4)
	v_perm_b32 v29, v33, v29, s43
	v_perm_b32 v28, v32, v28, s43
	s_waitcnt lgkmcnt(2)
	v_perm_b32 v30, v34, v30, s43
	s_waitcnt lgkmcnt(0)
	v_perm_b32 v31, v35, v31, s43
	s_nop 1
	v_mfma_f32_16x16x32_bf16 v[36:39], v[28:31], v[12:15], v[20:23]
	v_mfma_f32_16x16x32_bf16 v[40:43], v[28:31], v[16:19], v[24:27]
	s_nop 1
	ds_read_u16 v20, v148 offset:16608
	ds_read_u16 v21, v148 offset:17124
	ds_read_u16 v22, v148 offset:17640
	ds_read_u16 v23, v148 offset:18156
	ds_read_u16 v24, v148 offset:18672
	ds_read_u16 v25, v148 offset:19188
	ds_read_u16 v26, v148 offset:19704
	ds_read_u16 v27, v148 offset:20220
	s_waitcnt lgkmcnt(0)
	v_perm_b32 v27, v27, v26, s43
	v_perm_b32 v26, v25, v24, s43
	v_perm_b32 v25, v23, v22, s43
	v_perm_b32 v24, v21, v20, s43
	s_nop 1
	v_mfma_f32_16x16x32_bf16 v[20:23], v[24:27], v[12:15], v[2:5]
	v_mfma_f32_16x16x32_bf16 v[24:27], v[24:27], v[16:19], v[6:9]
	s_nop 1
	ds_read_u16 v2, v147 offset:33280
	ds_read_u16 v3, v147 offset:33796
	ds_read_u16 v4, v147 offset:34312
	ds_read_u16 v5, v147 offset:34828
	ds_read_u16 v6, v147 offset:35344
	ds_read_u16 v7, v147 offset:35860
	ds_read_u16 v8, v147 offset:36376
	ds_read_u16 v9, v147 offset:36892
	ds_read_u16 v12, v147 offset:33312
	ds_read_u16 v13, v147 offset:33828
	ds_read_u16 v14, v147 offset:34344
	ds_read_u16 v15, v147 offset:34860
	ds_read_u16 v16, v147 offset:35376
	ds_read_u16 v17, v147 offset:35892
	ds_read_u16 v18, v147 offset:36408
	ds_read_u16 v19, v147 offset:36924
	s_waitcnt lgkmcnt(8)
	v_perm_b32 v31, v9, v8, s43
	v_perm_b32 v30, v7, v6, s43
	v_perm_b32 v29, v5, v4, s43
	v_perm_b32 v28, v3, v2, s43
	ds_read_u16 v2, v148 offset:33024
	ds_read_u16 v6, v148 offset:33540
	ds_read_u16 v3, v148 offset:34056
	ds_read_u16 v7, v148 offset:34572
	ds_read_u16 v4, v148 offset:35088
	ds_read_u16 v8, v148 offset:35604
	ds_read_u16 v5, v148 offset:36120
	ds_read_u16 v9, v148 offset:36636
	s_waitcnt lgkmcnt(4)
	v_perm_b32 v3, v7, v3, s43
	v_perm_b32 v2, v6, v2, s43
	s_waitcnt lgkmcnt(2)
	v_perm_b32 v4, v8, v4, s43
	v_perm_b32 v35, v19, v18, s43
	s_waitcnt lgkmcnt(0)
	v_perm_b32 v5, v9, v5, s43
	v_perm_b32 v34, v17, v16, s43
	v_perm_b32 v33, v15, v14, s43
	v_perm_b32 v32, v13, v12, s43
	v_mfma_f32_16x16x32_bf16 v[12:15], v[2:5], v[28:31], v[44:47]
	s_nop 0
	v_mfma_f32_16x16x32_bf16 v[16:19], v[2:5], v[32:35], v[48:51]
	ds_read_u16 v2, v148 offset:33056
	ds_read_u16 v3, v148 offset:33572
	ds_read_u16 v4, v148 offset:34088
	ds_read_u16 v5, v148 offset:34604
	ds_read_u16 v6, v148 offset:35120
	ds_read_u16 v7, v148 offset:35636
	ds_read_u16 v8, v148 offset:36152
	ds_read_u16 v9, v148 offset:36668
	ds_read_u16 v44, v148 offset:33088
	ds_read_u16 v45, v148 offset:33604
	ds_read_u16 v46, v148 offset:34120
	ds_read_u16 v47, v148 offset:34636
	ds_read_u16 v48, v148 offset:35152
	ds_read_u16 v49, v148 offset:35668
	ds_read_u16 v50, v148 offset:36184
	ds_read_u16 v51, v148 offset:36700
	s_waitcnt lgkmcnt(8)
	v_perm_b32 v9, v9, v8, s43
	s_waitcnt lgkmcnt(0)
	v_perm_b32 v51, v51, v50, s43
	v_perm_b32 v50, v49, v48, s43
	v_perm_b32 v49, v47, v46, s43
	v_perm_b32 v48, v45, v44, s43
	v_perm_b32 v8, v7, v6, s43
	v_perm_b32 v7, v5, v4, s43
	v_mfma_f32_16x16x32_bf16 v[36:39], v[48:51], v[28:31], v[36:39]
	v_perm_b32 v6, v3, v2, s43
	v_mfma_f32_16x16x32_bf16 v[40:43], v[48:51], v[32:35], v[40:43]
	ds_read_u16 v44, v148 offset:33120
	ds_read_u16 v48, v148 offset:33636
	ds_read_u16 v45, v148 offset:34152
	ds_read_u16 v49, v148 offset:34668
	ds_read_u16 v46, v148 offset:35184
	ds_read_u16 v50, v148 offset:35700
	ds_read_u16 v47, v148 offset:36216
	ds_read_u16 v51, v148 offset:36732
	s_waitcnt lgkmcnt(4)
	v_perm_b32 v45, v49, v45, s43
	v_perm_b32 v44, v48, v44, s43
	s_waitcnt lgkmcnt(2)
	v_perm_b32 v46, v50, v46, s43
	v_mfma_f32_16x16x32_bf16 v[2:5], v[6:9], v[28:31], v[52:55]
	s_waitcnt lgkmcnt(0)
	v_perm_b32 v47, v51, v47, s43
	v_mfma_f32_16x16x32_bf16 v[6:9], v[6:9], v[32:35], v[56:59]
	s_nop 0
	v_mfma_f32_16x16x32_bf16 v[20:23], v[44:47], v[28:31], v[20:23]
	v_mfma_f32_16x16x32_bf16 v[24:27], v[44:47], v[32:35], v[24:27]
	ds_read_u16 v28, v147 offset:49792
	ds_read_u16 v29, v147 offset:50308
	ds_read_u16 v30, v147 offset:50824
	ds_read_u16 v31, v147 offset:51340
	ds_read_u16 v32, v147 offset:51856
	ds_read_u16 v33, v147 offset:52372
	ds_read_u16 v34, v147 offset:52888
	ds_read_u16 v35, v147 offset:53404
	ds_read_u16 v48, v147 offset:49824
	ds_read_u16 v52, v147 offset:50340
	ds_read_u16 v49, v147 offset:50856
	ds_read_u16 v53, v147 offset:51372
	ds_read_u16 v50, v147 offset:51888
	ds_read_u16 v54, v147 offset:52404
	ds_read_u16 v51, v147 offset:52920
	ds_read_u16 v55, v147 offset:53436
	s_waitcnt lgkmcnt(8)
	v_perm_b32 v47, v35, v34, s43
	v_perm_b32 v46, v33, v32, s43
	v_perm_b32 v45, v31, v30, s43
	v_perm_b32 v44, v29, v28, s43
	ds_read_u16 v28, v148 offset:49536
	ds_read_u16 v32, v148 offset:50052
	ds_read_u16 v29, v148 offset:50568
	ds_read_u16 v33, v148 offset:51084
	ds_read_u16 v30, v148 offset:51600
	ds_read_u16 v34, v148 offset:52116
	ds_read_u16 v31, v148 offset:52632
	ds_read_u16 v35, v148 offset:53148
	s_waitcnt lgkmcnt(4)
	v_perm_b32 v29, v33, v29, s43
	v_perm_b32 v28, v32, v28, s43
	s_waitcnt lgkmcnt(2)
	v_perm_b32 v30, v34, v30, s43
	v_perm_b32 v51, v55, v51, s43
	s_waitcnt lgkmcnt(0)
	v_perm_b32 v31, v35, v31, s43
	v_perm_b32 v50, v54, v50, s43
	v_perm_b32 v49, v53, v49, s43
	v_perm_b32 v48, v52, v48, s43
	v_mfma_f32_16x16x32_bf16 v[12:15], v[28:31], v[44:47], v[12:15]
	s_nop 0
	v_mfma_f32_16x16x32_bf16 v[16:19], v[28:31], v[48:51], v[16:19]
	ds_read_u16 v28, v148 offset:49568
	ds_read_u16 v32, v148 offset:50084
	ds_read_u16 v29, v148 offset:50600
	ds_read_u16 v33, v148 offset:51116
	ds_read_u16 v30, v148 offset:51632
	ds_read_u16 v34, v148 offset:52148
	ds_read_u16 v31, v148 offset:52664
	ds_read_u16 v35, v148 offset:53180
	s_waitcnt lgkmcnt(4)
	v_perm_b32 v29, v33, v29, s43
	v_perm_b32 v28, v32, v28, s43
	s_waitcnt lgkmcnt(2)
	v_perm_b32 v30, v34, v30, s43
	s_waitcnt lgkmcnt(0)
	v_perm_b32 v31, v35, v31, s43
	s_nop 1
	v_mfma_f32_16x16x32_bf16 v[2:5], v[28:31], v[44:47], v[2:5]
	v_mfma_f32_16x16x32_bf16 v[6:9], v[28:31], v[48:51], v[6:9]
	ds_read_u16 v28, v148 offset:49600
	ds_read_u16 v29, v148 offset:50116
	ds_read_u16 v30, v148 offset:50632
	ds_read_u16 v31, v148 offset:51148
	ds_read_u16 v32, v148 offset:51664
	ds_read_u16 v33, v148 offset:52180
	ds_read_u16 v34, v148 offset:52696
	ds_read_u16 v35, v148 offset:53212
	s_waitcnt lgkmcnt(0)
	v_perm_b32 v35, v35, v34, s43
	v_perm_b32 v34, v33, v32, s43
	v_perm_b32 v33, v31, v30, s43
	v_perm_b32 v32, v29, v28, s43
	s_nop 1
	v_mfma_f32_16x16x32_bf16 v[28:31], v[32:35], v[44:47], v[36:39]
	v_mfma_f32_16x16x32_bf16 v[32:35], v[32:35], v[48:51], v[40:43]
	s_nop 1
	ds_read_u16 v36, v148 offset:49632
	ds_read_u16 v40, v148 offset:50148
	ds_read_u16 v37, v148 offset:50664
	ds_read_u16 v41, v148 offset:51180
	ds_read_u16 v38, v148 offset:51696
	ds_read_u16 v42, v148 offset:52212
	ds_read_u16 v39, v148 offset:52728
	ds_read_u16 v43, v148 offset:53244
	s_waitcnt lgkmcnt(4)
	v_perm_b32 v37, v41, v37, s43
	v_perm_b32 v36, v40, v36, s43
	s_waitcnt lgkmcnt(2)
	v_perm_b32 v38, v42, v38, s43
	s_waitcnt lgkmcnt(0)
	v_perm_b32 v39, v43, v39, s43
	s_nop 1
	v_mfma_f32_16x16x32_bf16 v[20:23], v[36:39], v[44:47], v[20:23]
	v_mfma_f32_16x16x32_bf16 v[24:27], v[36:39], v[48:51], v[24:27]
	ds_read_u16 v36, v149
	ds_read_u16 v37, v149 offset:516
	ds_read_u16 v38, v149 offset:1032
	ds_read_u16 v39, v149 offset:1548
	ds_read_u16 v40, v149 offset:2064
	ds_read_u16 v41, v149 offset:2580
	ds_read_u16 v42, v149 offset:3096
	ds_read_u16 v43, v149 offset:3612
	ds_read_u16 v48, v149 offset:32
	ds_read_u16 v52, v149 offset:548
	ds_read_u16 v49, v149 offset:1064
	ds_read_u16 v53, v149 offset:1580
	ds_read_u16 v50, v149 offset:2096
	ds_read_u16 v54, v149 offset:2612
	ds_read_u16 v51, v149 offset:3128
	ds_read_u16 v55, v149 offset:3644
	s_waitcnt lgkmcnt(8)
	v_perm_b32 v47, v43, v42, s43
	v_perm_b32 v46, v41, v40, s43
	v_perm_b32 v45, v39, v38, s43
	v_perm_b32 v44, v37, v36, s43
	ds_read_u16 v36, v150
	ds_read_u16 v37, v150 offset:516
	ds_read_u16 v38, v150 offset:1032
	ds_read_u16 v39, v150 offset:1548
	ds_read_u16 v40, v150 offset:2064
	ds_read_u16 v41, v150 offset:2580
	ds_read_u16 v42, v150 offset:3096
	ds_read_u16 v43, v150 offset:3612
	s_waitcnt lgkmcnt(8)
	v_perm_b32 v51, v55, v51, s43
	v_perm_b32 v50, v54, v50, s43
	v_perm_b32 v49, v53, v49, s43
	v_perm_b32 v48, v52, v48, s43
	s_waitcnt lgkmcnt(0)
	v_perm_b32 v43, v43, v42, s43
	v_perm_b32 v42, v41, v40, s43
	v_perm_b32 v41, v39, v38, s43
	v_perm_b32 v40, v37, v36, s43
	s_nop 1
	v_mfma_f32_16x16x32_bf16 v[36:39], v[40:43], v[44:47], v[12:15]
	v_mfma_f32_16x16x32_bf16 v[40:43], v[40:43], v[48:51], v[16:19]
	s_nop 1
	ds_read_u16 v12, v150 offset:32
	ds_read_u16 v16, v150 offset:548
	ds_read_u16 v13, v150 offset:1064
	ds_read_u16 v17, v150 offset:1580
	ds_read_u16 v14, v150 offset:2096
	ds_read_u16 v18, v150 offset:2612
	ds_read_u16 v15, v150 offset:3128
	ds_read_u16 v19, v150 offset:3644
	s_waitcnt lgkmcnt(4)
	v_perm_b32 v13, v17, v13, s43
	v_perm_b32 v12, v16, v12, s43
	s_waitcnt lgkmcnt(2)
	v_perm_b32 v14, v18, v14, s43
	s_waitcnt lgkmcnt(0)
	v_perm_b32 v15, v19, v15, s43
	s_nop 1
	v_mfma_f32_16x16x32_bf16 v[2:5], v[12:15], v[44:47], v[2:5]
	v_mfma_f32_16x16x32_bf16 v[6:9], v[12:15], v[48:51], v[6:9]
	ds_read_u16 v12, v150 offset:64
	ds_read_u16 v13, v150 offset:580
	ds_read_u16 v14, v150 offset:1096
	ds_read_u16 v15, v150 offset:1612
	ds_read_u16 v16, v150 offset:2128
	ds_read_u16 v17, v150 offset:2644
	ds_read_u16 v18, v150 offset:3160
	ds_read_u16 v19, v150 offset:3676
	s_waitcnt lgkmcnt(0)
	v_perm_b32 v19, v19, v18, s43
	v_perm_b32 v18, v17, v16, s43
	v_perm_b32 v17, v15, v14, s43
	v_perm_b32 v16, v13, v12, s43
	s_nop 1
	v_mfma_f32_16x16x32_bf16 v[12:15], v[16:19], v[44:47], v[28:31]
	v_mfma_f32_16x16x32_bf16 v[16:19], v[16:19], v[48:51], v[32:35]
	s_nop 1
	ds_read_u16 v28, v150 offset:96
	ds_read_u16 v32, v150 offset:612
	ds_read_u16 v29, v150 offset:1128
	ds_read_u16 v33, v150 offset:1644
	ds_read_u16 v30, v150 offset:2160
	ds_read_u16 v34, v150 offset:2676
	ds_read_u16 v31, v150 offset:3192
	ds_read_u16 v35, v150 offset:3708
	s_waitcnt lgkmcnt(4)
	v_perm_b32 v29, v33, v29, s43
	v_perm_b32 v28, v32, v28, s43
	s_waitcnt lgkmcnt(2)
	v_perm_b32 v30, v34, v30, s43
	s_waitcnt lgkmcnt(0)
	v_perm_b32 v31, v35, v31, s43
	s_nop 1
	v_mfma_f32_16x16x32_bf16 v[20:23], v[28:31], v[44:47], v[20:23]
	v_mfma_f32_16x16x32_bf16 v[24:27], v[28:31], v[48:51], v[24:27]
	ds_read_u16 v28, v151
	ds_read_u16 v29, v151 offset:516
	ds_read_u16 v30, v151 offset:1032
	ds_read_u16 v31, v151 offset:1548
	ds_read_u16 v32, v151 offset:2064
	ds_read_u16 v33, v151 offset:2580
	ds_read_u16 v34, v151 offset:3096
	ds_read_u16 v35, v151 offset:3612
	ds_read_u16 v48, v151 offset:32
	ds_read_u16 v52, v151 offset:548
	ds_read_u16 v49, v151 offset:1064
	ds_read_u16 v53, v151 offset:1580
	ds_read_u16 v50, v151 offset:2096
	ds_read_u16 v54, v151 offset:2612
	ds_read_u16 v51, v151 offset:3128
	ds_read_u16 v55, v151 offset:3644
	s_waitcnt lgkmcnt(8)
	v_perm_b32 v47, v35, v34, s43
	v_perm_b32 v46, v33, v32, s43
	v_perm_b32 v45, v31, v30, s43
	v_perm_b32 v44, v29, v28, s43
	ds_read_u16 v28, v152 offset:516
	ds_read_u16 v29, v152 offset:1032
	ds_read_u16 v30, v152 offset:1548
	ds_read_u16 v31, v152 offset:2064
	ds_read_u16 v32, v152 offset:2580
	ds_read_u16 v33, v152 offset:3096
	ds_read_u16 v34, v152 offset:3612
	s_waitcnt lgkmcnt(13)
	v_perm_b32 v48, v52, v48, s43
	s_waitcnt lgkmcnt(7)
	v_perm_b32 v51, v55, v51, s43
	v_perm_b32 v50, v54, v50, s43
	v_perm_b32 v49, v53, v49, s43
	s_waitcnt lgkmcnt(0)
	v_perm_b32 v35, v34, v33, s43
	v_perm_b32 v33, v30, v29, s43
	ds_read_u16 v29, v152
	ds_read_u16 v52, v152 offset:32
	v_perm_b32 v34, v32, v31, s43
	s_waitcnt lgkmcnt(1)
	v_perm_b32 v32, v28, v29, s43
	s_nop 1
	v_mfma_f32_16x16x32_bf16 v[28:31], v[32:35], v[44:47], v[36:39]
	v_mfma_f32_16x16x32_bf16 v[32:35], v[32:35], v[48:51], v[40:43]
	s_nop 1
	ds_read_u16 v36, v152 offset:548
	ds_read_u16 v37, v152 offset:1064
	ds_read_u16 v40, v152 offset:1580
	ds_read_u16 v38, v152 offset:2096
	ds_read_u16 v41, v152 offset:2612
	ds_read_u16 v39, v152 offset:3128
	ds_read_u16 v42, v152 offset:3644
	s_waitcnt lgkmcnt(4)
	v_perm_b32 v37, v40, v37, s43
	v_perm_b32 v36, v36, v52, s43
	s_waitcnt lgkmcnt(2)
	v_perm_b32 v38, v41, v38, s43
	s_waitcnt lgkmcnt(0)
	v_perm_b32 v39, v42, v39, s43
	s_nop 1
	v_mfma_f32_16x16x32_bf16 v[2:5], v[36:39], v[44:47], v[2:5]
	v_mfma_f32_16x16x32_bf16 v[6:9], v[36:39], v[48:51], v[6:9]
	ds_read_u16 v36, v152 offset:64
	ds_read_u16 v40, v152 offset:580
	ds_read_u16 v37, v152 offset:1096
	ds_read_u16 v41, v152 offset:1612
	ds_read_u16 v38, v152 offset:2128
	ds_read_u16 v42, v152 offset:2644
	ds_read_u16 v39, v152 offset:3160
	ds_read_u16 v43, v152 offset:3676
	s_waitcnt lgkmcnt(4)
	v_perm_b32 v37, v41, v37, s43
	v_perm_b32 v36, v40, v36, s43
	s_waitcnt lgkmcnt(2)
	v_perm_b32 v38, v42, v38, s43
	s_waitcnt lgkmcnt(0)
	v_perm_b32 v39, v43, v39, s43
	s_nop 1
	v_mfma_f32_16x16x32_bf16 v[12:15], v[36:39], v[44:47], v[12:15]
	v_mfma_f32_16x16x32_bf16 v[16:19], v[36:39], v[48:51], v[16:19]
	ds_read_u16 v36, v152 offset:96
	ds_read_u16 v40, v152 offset:612
	ds_read_u16 v37, v152 offset:1128
	ds_read_u16 v41, v152 offset:1644
	ds_read_u16 v38, v152 offset:2160
	ds_read_u16 v42, v152 offset:2676
	ds_read_u16 v39, v152 offset:3192
	ds_read_u16 v43, v152 offset:3708
	s_waitcnt lgkmcnt(4)
	v_perm_b32 v37, v41, v37, s43
	v_perm_b32 v36, v40, v36, s43
	s_waitcnt lgkmcnt(2)
	v_perm_b32 v38, v42, v38, s43
	s_waitcnt lgkmcnt(0)
	v_perm_b32 v39, v43, v39, s43
	s_nop 1
	v_mfma_f32_16x16x32_bf16 v[20:23], v[36:39], v[44:47], v[20:23]
	v_mfma_f32_16x16x32_bf16 v[24:27], v[36:39], v[48:51], v[24:27]
	ds_read_u16 v36, v153 offset:516
	ds_read_u16 v37, v153 offset:1032
	ds_read_u16 v40, v153 offset:1548
	ds_read_u16 v38, v153 offset:2064
	ds_read_u16 v41, v153 offset:2580
	ds_read_u16 v39, v153 offset:3096
	ds_read_u16 v42, v153 offset:3612
	ds_read_u16 v43, v153
	ds_read_u16 v44, v153 offset:32
	ds_read_u16 v45, v153 offset:548
	ds_read_u16 v46, v153 offset:1064
	ds_read_u16 v47, v153 offset:1580
	ds_read_u16 v48, v153 offset:2096
	ds_read_u16 v49, v153 offset:2612
	ds_read_u16 v50, v153 offset:3128
	ds_read_u16 v51, v153 offset:3644
	s_waitcnt lgkmcnt(9)
	v_perm_b32 v39, v42, v39, s43
	v_perm_b32 v38, v41, v38, s43
	v_perm_b32 v37, v40, v37, s43
	s_waitcnt lgkmcnt(8)
	v_perm_b32 v36, v36, v43, s43
	s_waitcnt lgkmcnt(0)
	v_perm_b32 v43, v51, v50, s43
	v_perm_b32 v42, v49, v48, s43
	v_perm_b32 v41, v47, v46, s43
	v_perm_b32 v40, v45, v44, s43
	ds_read_u16 v44, v154 offset:516
	ds_read_u16 v45, v154 offset:1032
	ds_read_u16 v48, v154 offset:1548
	ds_read_u16 v46, v154 offset:2064
	ds_read_u16 v49, v154 offset:2580
	ds_read_u16 v47, v154 offset:3096
	ds_read_u16 v50, v154 offset:3612
	s_waitcnt lgkmcnt(4)
	v_perm_b32 v45, v48, v45, s43
	s_waitcnt lgkmcnt(2)
	v_perm_b32 v46, v49, v46, s43
	ds_read_u16 v48, v154
	ds_read_u16 v49, v154 offset:32
	s_waitcnt lgkmcnt(2)
	v_perm_b32 v47, v50, v47, s43
	s_waitcnt lgkmcnt(1)
	v_perm_b32 v44, v44, v48, s43
	s_nop 1
	v_mfma_f32_16x16x32_bf16 v[28:31], v[44:47], v[36:39], v[28:31]
	v_mfma_f32_16x16x32_bf16 v[32:35], v[44:47], v[40:43], v[32:35]
	ds_read_u16 v44, v154 offset:548
	ds_read_u16 v45, v154 offset:1064
	ds_read_u16 v48, v154 offset:1580
	ds_read_u16 v46, v154 offset:2096
	ds_read_u16 v50, v154 offset:2612
	ds_read_u16 v47, v154 offset:3128
	ds_read_u16 v51, v154 offset:3644
	s_waitcnt lgkmcnt(4)
	v_perm_b32 v45, v48, v45, s43
	v_perm_b32 v44, v44, v49, s43
	s_waitcnt lgkmcnt(2)
	v_perm_b32 v46, v50, v46, s43
	s_waitcnt lgkmcnt(0)
	v_perm_b32 v47, v51, v47, s43
	s_nop 1
	v_mfma_f32_16x16x32_bf16 v[2:5], v[44:47], v[36:39], v[2:5]
	v_mfma_f32_16x16x32_bf16 v[6:9], v[44:47], v[40:43], v[6:9]
	ds_read_u16 v44, v154 offset:64
	ds_read_u16 v48, v154 offset:580
	ds_read_u16 v45, v154 offset:1096
	ds_read_u16 v49, v154 offset:1612
	ds_read_u16 v46, v154 offset:2128
	ds_read_u16 v50, v154 offset:2644
	ds_read_u16 v47, v154 offset:3160
	ds_read_u16 v51, v154 offset:3676
	s_waitcnt lgkmcnt(4)
	v_perm_b32 v45, v49, v45, s43
	v_perm_b32 v44, v48, v44, s43
	s_waitcnt lgkmcnt(2)
	v_perm_b32 v46, v50, v46, s43
	s_waitcnt lgkmcnt(0)
	v_perm_b32 v47, v51, v47, s43
	s_nop 1
	v_mfma_f32_16x16x32_bf16 v[12:15], v[44:47], v[36:39], v[12:15]
	v_mfma_f32_16x16x32_bf16 v[16:19], v[44:47], v[40:43], v[16:19]
	ds_read_u16 v44, v154 offset:96
	ds_read_u16 v48, v154 offset:612
	ds_read_u16 v45, v154 offset:1128
	ds_read_u16 v49, v154 offset:1644
	ds_read_u16 v46, v154 offset:2160
	ds_read_u16 v50, v154 offset:2676
	ds_read_u16 v47, v154 offset:3192
	ds_read_u16 v51, v154 offset:3708
	s_waitcnt lgkmcnt(4)
	v_perm_b32 v45, v49, v45, s43
	v_perm_b32 v44, v48, v44, s43
	s_waitcnt lgkmcnt(2)
	v_perm_b32 v46, v50, v46, s43
	s_waitcnt lgkmcnt(0)
	v_perm_b32 v47, v51, v47, s43
	s_nop 1
	v_mfma_f32_16x16x32_bf16 v[20:23], v[44:47], v[36:39], v[20:23]
	v_mfma_f32_16x16x32_bf16 v[24:27], v[44:47], v[40:43], v[24:27]
	ds_read_u16 v36, v155 offset:516
	ds_read_u16 v37, v155 offset:1032
	ds_read_u16 v40, v155 offset:1548
	ds_read_u16 v38, v155 offset:2064
	ds_read_u16 v41, v155 offset:2580
	ds_read_u16 v39, v155 offset:3096
	ds_read_u16 v42, v155 offset:3612
	ds_read_u16 v43, v155
	ds_read_u16 v44, v155 offset:32
	ds_read_u16 v45, v155 offset:548
	ds_read_u16 v46, v155 offset:1064
	ds_read_u16 v47, v155 offset:1580
	ds_read_u16 v48, v155 offset:2096
	ds_read_u16 v49, v155 offset:2612
	ds_read_u16 v50, v155 offset:3128
	ds_read_u16 v51, v155 offset:3644
	s_waitcnt lgkmcnt(9)
	v_perm_b32 v39, v42, v39, s43
	v_perm_b32 v38, v41, v38, s43
	v_perm_b32 v37, v40, v37, s43
	s_waitcnt lgkmcnt(8)
	v_perm_b32 v36, v36, v43, s43
	s_waitcnt lgkmcnt(0)
	v_perm_b32 v43, v51, v50, s43
	v_perm_b32 v42, v49, v48, s43
	v_perm_b32 v41, v47, v46, s43
	v_perm_b32 v40, v45, v44, s43
	ds_read_u16 v44, v156 offset:516
	ds_read_u16 v45, v156 offset:1032
	ds_read_u16 v46, v156 offset:1548
	ds_read_u16 v47, v156 offset:2064
	ds_read_u16 v48, v156 offset:2580
	ds_read_u16 v49, v156 offset:3096
	ds_read_u16 v50, v156 offset:3612
	s_waitcnt lgkmcnt(0)
	v_perm_b32 v51, v50, v49, s43
	v_perm_b32 v49, v46, v45, s43
	ds_read_u16 v45, v156
	ds_read_u16 v52, v156 offset:32
	v_perm_b32 v50, v48, v47, s43
	s_waitcnt lgkmcnt(1)
	v_perm_b32 v48, v44, v45, s43
	s_nop 1
	v_mfma_f32_16x16x32_bf16 v[44:47], v[48:51], v[36:39], v[28:31]
	v_mfma_f32_16x16x32_bf16 v[28:31], v[48:51], v[40:43], v[32:35]
	s_nop 2
	ds_read_u16 v32, v156 offset:548
	ds_read_u16 v33, v156 offset:1064
	ds_read_u16 v34, v156 offset:1580
	ds_read_u16 v35, v156 offset:2096
	ds_read_u16 v48, v156 offset:2612
	ds_read_u16 v49, v156 offset:3128
	ds_read_u16 v50, v156 offset:3644
	s_waitcnt lgkmcnt(0)
	v_perm_b32 v51, v50, v49, s43
	v_perm_b32 v50, v48, v35, s43
	v_perm_b32 v49, v34, v33, s43
	v_perm_b32 v48, v32, v52, s43
	s_nop 1
	v_mfma_f32_16x16x32_bf16 v[32:35], v[48:51], v[36:39], v[2:5]
	v_mfma_f32_16x16x32_bf16 v[2:5], v[48:51], v[40:43], v[6:9]
	s_nop 2
	ds_read_u16 v6, v156 offset:64
	ds_read_u16 v48, v156 offset:580
	ds_read_u16 v7, v156 offset:1096
	ds_read_u16 v49, v156 offset:1612
	ds_read_u16 v8, v156 offset:2128
	ds_read_u16 v50, v156 offset:2644
	ds_read_u16 v9, v156 offset:3160
	ds_read_u16 v51, v156 offset:3676
	s_waitcnt lgkmcnt(4)
	v_perm_b32 v7, v49, v7, s43
	v_perm_b32 v6, v48, v6, s43
	s_waitcnt lgkmcnt(2)
	v_perm_b32 v8, v50, v8, s43
	s_waitcnt lgkmcnt(0)
	v_perm_b32 v9, v51, v9, s43
	s_nop 1
	v_mfma_f32_16x16x32_bf16 v[12:15], v[6:9], v[36:39], v[12:15]
	v_mfma_f32_16x16x32_bf16 v[6:9], v[6:9], v[40:43], v[16:19]
	s_nop 2
	ds_read_u16 v16, v156 offset:96
	ds_read_u16 v48, v156 offset:612
	ds_read_u16 v17, v156 offset:1128
	ds_read_u16 v49, v156 offset:1644
	ds_read_u16 v18, v156 offset:2160
	ds_read_u16 v50, v156 offset:2676
	ds_read_u16 v19, v156 offset:3192
	ds_read_u16 v51, v156 offset:3708
	s_waitcnt lgkmcnt(4)
	v_perm_b32 v17, v49, v17, s43
	v_perm_b32 v16, v48, v16, s43
	s_waitcnt lgkmcnt(2)
	v_perm_b32 v18, v50, v18, s43
	s_waitcnt lgkmcnt(0)
	v_perm_b32 v19, v51, v19, s43
	s_nop 1
	v_mfma_f32_16x16x32_bf16 v[20:23], v[16:19], v[36:39], v[20:23]
	v_mfma_f32_16x16x32_bf16 v[16:19], v[16:19], v[40:43], v[24:27]
	s_nop 2
	v_lshl_add_u64 v[24:25], s[4:5], 0, v[72:73]
	s_lshl_b64 s[4:5], s[48:49], 23
	s_add_u32 s2, s34, s2
	s_addc_u32 s30, s35, 0
	s_add_u32 s4, s2, s4
	v_lshlrev_b64 v[24:25], 15, v[24:25]
	s_addc_u32 s5, s30, s5
	v_lshl_add_u64 v[24:25], s[4:5], 0, v[24:25]
	s_mov_b64 s[4:5], 0x16100000
	v_lshl_add_u64 v[24:25], v[24:25], 0, s[4:5]
	v_lshl_add_u64 v[26:27], v[24:25], 0, v[80:81]
	global_store_dword v[26:27], v44, off
	global_store_dword v[26:27], v45, off offset:512
	global_store_dword v[26:27], v46, off offset:1024
	global_store_dword v[26:27], v47, off offset:1536
	global_store_dword v[26:27], v28, off offset:64
	v_lshl_add_u64 v[26:27], v[24:25], 0, v[82:83]
	global_store_dword v[26:27], v29, off offset:64
	v_lshl_add_u64 v[26:27], v[24:25], 0, v[84:85]
	global_store_dword v[26:27], v30, off offset:64
	v_lshl_add_u64 v[26:27], v[24:25], 0, v[86:87]
	global_store_dword v[26:27], v31, off offset:64
	v_lshl_add_u64 v[26:27], v[24:25], 0, v[88:89]
	v_lshl_add_u64 v[28:29], v[24:25], 0, v[90:91]
	global_store_dword v[26:27], v32, off
	global_store_dword v[28:29], v33, off
	v_lshl_add_u64 v[30:31], v[24:25], 0, v[92:93]
	v_lshl_add_u64 v[32:33], v[24:25], 0, v[94:95]
	global_store_dword v[30:31], v34, off
	global_store_dword v[32:33], v35, off
	global_store_dword v[26:27], v2, off offset:64
	global_store_dword v[28:29], v3, off offset:64
	global_store_dword v[30:31], v4, off offset:64
	global_store_dword v[32:33], v5, off offset:64
	v_lshl_add_u64 v[2:3], v[24:25], 0, v[96:97]
	v_lshl_add_u64 v[4:5], v[24:25], 0, v[98:99]
	global_store_dword v[2:3], v12, off
	global_store_dword v[4:5], v13, off
	v_lshl_add_u64 v[12:13], v[24:25], 0, v[100:101]
	v_lshl_add_u64 v[26:27], v[24:25], 0, v[102:103]
	global_store_dword v[12:13], v14, off
	global_store_dword v[26:27], v15, off
	global_store_dword v[2:3], v6, off offset:64
	global_store_dword v[4:5], v7, off offset:64
	global_store_dword v[12:13], v8, off offset:64
	global_store_dword v[26:27], v9, off offset:64
	v_lshl_add_u64 v[2:3], v[24:25], 0, v[104:105]
	v_lshl_add_u64 v[4:5], v[24:25], 0, v[106:107]
	v_lshl_add_u64 v[6:7], v[24:25], 0, v[108:109]
	v_lshl_add_u64 v[8:9], v[24:25], 0, v[110:111]
	s_mov_b64 s[30:31], 0
	global_store_dword v[2:3], v20, off
	global_store_dword v[4:5], v21, off
	global_store_dword v[6:7], v22, off
	global_store_dword v[8:9], v23, off
	global_store_dword v[2:3], v16, off offset:64
	global_store_dword v[4:5], v17, off offset:64
	global_store_dword v[6:7], v18, off offset:64
	global_store_dword v[8:9], v19, off offset:64
	s_barrier
